# on top of v62: weight-transposition tile loops (P0, P2) wait only for the tile loads (counted vmcnt) instead of also draining the previous tile's store acknowledgements
# baseline (speedup 1.0000x reference)
.LBB0_151:
	s_movk_i32 s6, 0x104
	v_mul_lo_u32 v3, v41, s6
	v_add_lshl_u32 v60, v3, v1, 1
	v_mul_lo_u32 v3, v43, s6
	v_add_lshl_u32 v61, v3, v1, 1
	v_mul_lo_u32 v3, v45, s6
	v_add_lshl_u32 v62, v3, v1, 1
	v_mul_lo_u32 v3, v47, s6
	v_add_lshl_u32 v63, v3, v1, 1
	v_mul_lo_u32 v3, v49, s6
	v_add_lshl_u32 v64, v3, v1, 1
	v_mul_lo_u32 v3, v51, s6
	v_add_lshl_u32 v65, v3, v1, 1
	v_mul_lo_u32 v3, v58, s6
	v_add_lshl_u32 v66, v3, v1, 1
	v_mul_lo_u32 v3, v59, s6
	s_waitcnt lgkmcnt(0)
	s_add_u32 s14, s10, s14
	v_add_lshl_u32 v67, v3, v1, 1
	v_lshlrev_b32_e32 v3, 3, v53
	s_addc_u32 s15, s11, s15
	v_and_b32_e32 v38, 56, v3
	v_mul_u32_u24_e32 v68, 0x208, v38
	v_mov_b32_e32 v5, 0
	v_ashrrev_i32_e32 v69, 3, v53
	v_ashrrev_i32_e32 v70, 3, v54
	v_ashrrev_i32_e32 v71, 3, v55
	v_ashrrev_i32_e32 v72, 3, v56
	s_mov_b32 s17, 0
	s_movk_i32 s65, 0xc00
	v_mov_b32_e32 v73, 0xffffff80
	s_mov_b32 s66, 0
	s_mov_b32 s67, s2
	s_mov_b64 s[6:7], s[14:15]
	s_mov_b32 s16, s64
	s_mov_b32 s69, s62
	s_mov_b32 s68, s3
	s_mov_b32 s70, s63
	s_waitcnt vmcnt(0)
	s_branch .LBB0_153

.LBB0_153:
	s_mul_i32 s8, s66, 0x8200
	s_add_i32 s13, s8, 0
	s_waitcnt vmcnt(2)
	v_pk_mul_f32 v[54:55], v[6:7], v[40:41] op_sel_hi:[1,0]
	v_pk_mul_f32 v[56:57], v[8:9], v[40:41] op_sel_hi:[1,0]
	v_cvt_pk_bf16_f32 v54, v54, v55
	v_cvt_pk_bf16_f32 v55, v56, v57
	v_add_u32_e32 v3, s13, v60
	ds_write_b64 v3, v[54:55]
	v_pk_mul_f32 v[54:55], v[42:43], v[10:11] op_sel_hi:[0,1]
	v_pk_mul_f32 v[56:57], v[42:43], v[12:13] op_sel_hi:[0,1]
	v_cvt_pk_bf16_f32 v54, v54, v55
	v_cvt_pk_bf16_f32 v55, v56, v57
	v_add_u32_e32 v3, s13, v61
	ds_write_b64 v3, v[54:55]
	v_pk_mul_f32 v[54:55], v[44:45], v[14:15] op_sel_hi:[0,1]
	v_pk_mul_f32 v[56:57], v[44:45], v[16:17] op_sel_hi:[0,1]
	v_cvt_pk_bf16_f32 v54, v54, v55
	v_cvt_pk_bf16_f32 v55, v56, v57
	v_add_u32_e32 v3, s13, v62
	ds_write_b64 v3, v[54:55]
	v_pk_mul_f32 v[54:55], v[46:47], v[18:19] op_sel_hi:[0,1]
	v_pk_mul_f32 v[56:57], v[46:47], v[20:21] op_sel_hi:[0,1]
	v_cvt_pk_bf16_f32 v54, v54, v55
	v_cvt_pk_bf16_f32 v55, v56, v57
	v_add_u32_e32 v3, s13, v63
	ds_write_b64 v3, v[54:55]
	v_pk_mul_f32 v[54:55], v[48:49], v[22:23] op_sel_hi:[0,1]
	v_pk_mul_f32 v[56:57], v[48:49], v[24:25] op_sel_hi:[0,1]
	v_cvt_pk_bf16_f32 v54, v54, v55
	v_cvt_pk_bf16_f32 v55, v56, v57
	v_add_u32_e32 v3, s13, v64
	ds_write_b64 v3, v[54:55]
	v_pk_mul_f32 v[54:55], v[50:51], v[26:27] op_sel_hi:[0,1]
	v_pk_mul_f32 v[56:57], v[50:51], v[28:29] op_sel_hi:[0,1]
	v_cvt_pk_bf16_f32 v54, v54, v55
	v_cvt_pk_bf16_f32 v55, v56, v57
	v_add_u32_e32 v3, s13, v65
	ds_write_b64 v3, v[54:55]
	v_pk_mul_f32 v[54:55], v[52:53], v[30:31] op_sel_hi:[0,1]
	v_pk_mul_f32 v[56:57], v[52:53], v[32:33] op_sel_hi:[0,1]
	s_add_i32 s67, s67, s33
	v_cvt_pk_bf16_f32 v54, v54, v55
	v_cvt_pk_bf16_f32 v55, v56, v57
	v_add_u32_e32 v3, s13, v66
	s_cmpk_gt_i32 s67, 0x4bf
	ds_write_b64 v3, v[54:55]
	v_pk_mul_f32 v[54:55], v[2:3], v[34:35] op_sel_hi:[0,1]
	v_pk_mul_f32 v[56:57], v[2:3], v[36:37] op_sel_hi:[0,1]
	s_cselect_b64 s[18:19], -1, 0
	v_cvt_pk_bf16_f32 v54, v54, v55
	v_cvt_pk_bf16_f32 v55, v56, v57
	v_add_u32_e32 v3, s13, v67
	s_and_b64 vcc, exec, s[18:19]
	s_mov_b32 s30, s12
	ds_write_b64 v3, v[54:55]
	s_cbranch_vccnz .LBB0_293
	s_add_i32 s6, s67, 0x1460
	s_cmpk_lt_i32 s67, 0x340
	s_cselect_b32 s73, s67, s6
	s_cmpk_gt_i32 s73, 0x33f
	s_cselect_b64 s[6:7], -1, 0
	s_cmpk_gt_i32 s73, 0x43f
	s_cselect_b64 s[8:9], -1, 0
	v_cndmask_b32_e64 v2, 0, 1, s[8:9]
	s_cmp_lg_u64 s[6:7], 0
	v_readfirstlane_b32 s16, v2
	s_addc_u32 s16, s16, 0
	s_cmpk_gt_i32 s73, 0x53f
	s_cselect_b64 s[24:25], -1, 0
	s_cmpk_gt_i32 s73, 0xabf
	v_cndmask_b32_e64 v2, 0, 1, s[24:25]
	s_cselect_b64 s[26:27], -1, 0
	v_readfirstlane_b32 s20, v2
	s_cmp_lg_u64 s[26:27], 0
	s_addc_u32 s16, s16, s20
	s_cmpk_gt_i32 s73, 0x103f
	s_cselect_b64 s[28:29], -1, 0
	s_cmpk_gt_i32 s73, 0x12ff
	v_cndmask_b32_e64 v2, 0, 1, s[28:29]
	s_cselect_b64 s[30:31], -1, 0
	v_readfirstlane_b32 s20, v2
	s_cmp_lg_u64 s[30:31], 0
	s_addc_u32 s16, s16, s20
	s_cmpk_gt_i32 s73, 0x15bf
	s_cselect_b64 s[34:35], -1, 0
	s_cmpk_gt_i32 s73, 0x167f
	v_cndmask_b32_e64 v2, 0, 1, s[34:35]
	s_cselect_b64 s[36:37], -1, 0
	v_readfirstlane_b32 s20, v2
	s_cmp_lg_u64 s[36:37], 0
	s_addc_u32 s16, s16, s20
	s_cmpk_gt_i32 s73, 0x16bf
	s_cselect_b64 s[38:39], -1, 0
	s_cmpk_gt_i32 s73, 0x16df
	v_cndmask_b32_e64 v2, 0, 1, s[38:39]
	s_cselect_b64 s[40:41], -1, 0
	v_readfirstlane_b32 s20, v2
	s_cmp_lg_u64 s[40:41], 0
	s_addc_u32 s16, s16, s20
	s_cmpk_gt_i32 s73, 0x179f
	s_cselect_b64 s[42:43], -1, 0
	s_cmpk_gt_i32 s73, 0x181f
	v_cndmask_b32_e64 v2, 0, 1, s[42:43]
	s_cselect_b64 s[44:45], -1, 0
	v_readfirstlane_b32 s20, v2
	s_cmp_lg_u64 s[44:45], 0
	s_addc_u32 s16, s16, s20
	s_cmpk_gt_i32 s73, 0x189f
	s_cselect_b64 s[46:47], -1, 0
	s_cmpk_gt_i32 s73, 0x18bf
	v_cndmask_b32_e64 v2, 0, 1, s[46:47]
	s_cselect_b64 s[48:49], -1, 0
	v_readfirstlane_b32 s20, v2
	s_cmp_lg_u64 s[48:49], 0
	s_addc_u32 s16, s16, s20
	s_cmpk_gt_i32 s73, 0x18df
	s_cselect_b64 s[50:51], -1, 0
	s_cmpk_gt_i32 s73, 0x18ff
	v_cndmask_b32_e64 v2, 0, 1, s[50:51]
	s_cselect_b64 s[52:53], -1, 0
	v_readfirstlane_b32 s20, v2
	s_cmp_lg_u64 s[52:53], 0
	s_addc_u32 s74, s16, s20
	s_cmp_lg_u32 s74, 1
	s_cbranch_scc1 .LBB0_156
	s_mov_b64 s[20:21], 0x1b00000
	s_mov_b32 s16, -1
	s_movk_i32 s71, 0x800
	s_mov_b64 s[22:23], 14
	s_mov_b64 s[56:57], 0
	s_cmp_lg_u32 s74, 2
	s_mov_b64 s[54:55], 0
	s_cbranch_scc0 .LBB0_157
	s_branch .LBB0_158

.LBB0_1398:
	s_movk_i32 s6, 0x104
	v_mul_lo_u32 v11, v45, s6
	v_add_lshl_u32 v62, v11, v41, 1
	v_mul_lo_u32 v11, v47, s6
	v_add_lshl_u32 v63, v11, v41, 1
	v_mul_lo_u32 v11, v49, s6
	v_add_lshl_u32 v64, v11, v41, 1
	v_mul_lo_u32 v11, v51, s6
	v_add_lshl_u32 v65, v11, v41, 1
	v_mul_lo_u32 v11, v58, s6
	v_add_lshl_u32 v66, v11, v41, 1
	v_mul_lo_u32 v11, v59, s6
	v_add_lshl_u32 v67, v11, v41, 1
	v_mul_lo_u32 v11, v60, s6
	v_add_lshl_u32 v68, v11, v41, 1
	v_mul_lo_u32 v11, v61, s6
	s_waitcnt lgkmcnt(0)
	s_add_u32 s14, s0, s14
	v_add_lshl_u32 v69, v11, v41, 1
	v_lshlrev_b32_e32 v11, 3, v39
	s_addc_u32 s15, s1, s15
	v_and_b32_e32 v40, 56, v11
	v_mul_u32_u24_e32 v70, 0x208, v40
	v_mov_b32_e32 v13, 0
	v_ashrrev_i32_e32 v39, 3, v39
	v_ashrrev_i32_e32 v71, 3, v53
	v_ashrrev_i32_e32 v72, 3, v54
	v_ashrrev_i32_e32 v73, 3, v55
	s_mov_b32 s17, 0
	s_movk_i32 s53, 0xc00
	v_mov_b32_e32 v74, 0xffffff80
	s_mov_b32 s54, 0
	s_mov_b64 s[6:7], s[14:15]
	s_mov_b32 s16, s52
	s_mov_b32 s58, s50
	s_mov_b32 s57, s3
	s_mov_b32 s59, s51
	s_waitcnt vmcnt(0)
	s_branch .LBB0_1400

.LBB0_1400:
	s_mul_i32 s8, s54, 0x8200
	s_add_i32 s13, s8, 0
	s_waitcnt vmcnt(4)
	v_pk_mul_f32 v[54:55], v[2:3], v[38:39] op_sel_hi:[1,0]
	v_pk_mul_f32 v[56:57], v[4:5], v[38:39] op_sel_hi:[1,0]
	v_cvt_pk_bf16_f32 v54, v54, v55
	v_cvt_pk_bf16_f32 v55, v56, v57
	v_add_u32_e32 v11, s13, v62
	ds_write_b64 v11, v[54:55]
	v_pk_mul_f32 v[54:55], v[42:43], v[6:7] op_sel_hi:[0,1]
	v_pk_mul_f32 v[56:57], v[42:43], v[8:9] op_sel_hi:[0,1]
	v_cvt_pk_bf16_f32 v54, v54, v55
	v_cvt_pk_bf16_f32 v55, v56, v57
	v_add_u32_e32 v11, s13, v63
	ds_write_b64 v11, v[54:55]
	v_pk_mul_f32 v[54:55], v[44:45], v[14:15] op_sel_hi:[0,1]
	v_pk_mul_f32 v[56:57], v[44:45], v[16:17] op_sel_hi:[0,1]
	v_cvt_pk_bf16_f32 v54, v54, v55
	v_cvt_pk_bf16_f32 v55, v56, v57
	v_add_u32_e32 v11, s13, v64
	ds_write_b64 v11, v[54:55]
	v_pk_mul_f32 v[54:55], v[46:47], v[18:19] op_sel_hi:[0,1]
	v_pk_mul_f32 v[56:57], v[46:47], v[20:21] op_sel_hi:[0,1]
	v_cvt_pk_bf16_f32 v54, v54, v55
	v_cvt_pk_bf16_f32 v55, v56, v57
	v_add_u32_e32 v11, s13, v65
	ds_write_b64 v11, v[54:55]
	v_pk_mul_f32 v[54:55], v[48:49], v[22:23] op_sel_hi:[0,1]
	v_pk_mul_f32 v[56:57], v[48:49], v[24:25] op_sel_hi:[0,1]
	v_cvt_pk_bf16_f32 v54, v54, v55
	v_cvt_pk_bf16_f32 v55, v56, v57
	v_add_u32_e32 v11, s13, v66
	ds_write_b64 v11, v[54:55]
	v_pk_mul_f32 v[54:55], v[50:51], v[26:27] op_sel_hi:[0,1]
	v_pk_mul_f32 v[56:57], v[50:51], v[28:29] op_sel_hi:[0,1]
	v_cvt_pk_bf16_f32 v54, v54, v55
	v_cvt_pk_bf16_f32 v55, v56, v57
	v_add_u32_e32 v11, s13, v67
	ds_write_b64 v11, v[54:55]
	v_pk_mul_f32 v[54:55], v[52:53], v[30:31] op_sel_hi:[0,1]
	v_pk_mul_f32 v[56:57], v[52:53], v[32:33] op_sel_hi:[0,1]
	s_add_i32 s56, s55, s33
	v_cvt_pk_bf16_f32 v54, v54, v55
	v_cvt_pk_bf16_f32 v55, v56, v57
	v_add_u32_e32 v11, s13, v68
	s_cmpk_gt_i32 s56, 0x179f
	ds_write_b64 v11, v[54:55]
	v_pk_mul_f32 v[54:55], v[10:11], v[34:35] op_sel_hi:[0,1]
	v_pk_mul_f32 v[56:57], v[10:11], v[36:37] op_sel_hi:[0,1]
	s_cselect_b64 s[18:19], -1, 0
	v_cvt_pk_bf16_f32 v54, v54, v55
	v_cvt_pk_bf16_f32 v55, v56, v57
	v_add_u32_e32 v11, s13, v69
	s_and_b64 vcc, exec, s[18:19]
	s_mov_b32 s30, s12
	ds_write_b64 v11, v[54:55]
	s_cbranch_vccnz .LBB0_1528
	s_cmpk_gt_i32 s56, 0x33f
	s_cselect_b64 s[6:7], -1, 0
	s_cmpk_gt_i32 s56, 0x43f
	s_cselect_b64 s[8:9], -1, 0
	v_cndmask_b32_e64 v2, 0, 1, s[8:9]
	s_cmp_lg_u64 s[6:7], 0
	v_readfirstlane_b32 s16, v2
	s_addc_u32 s16, s16, 0
	s_cmpk_gt_i32 s56, 0x53f
	s_cselect_b64 s[24:25], -1, 0
	s_cmpk_gt_i32 s56, 0xabf
	v_cndmask_b32_e64 v2, 0, 1, s[24:25]
	s_cselect_b64 s[26:27], -1, 0
	v_readfirstlane_b32 s20, v2
	s_cmp_lg_u64 s[26:27], 0
	s_addc_u32 s16, s16, s20
	s_cmpk_gt_i32 s56, 0x103f
	s_cselect_b64 s[28:29], -1, 0
	s_cmpk_gt_i32 s56, 0x12ff
	v_cndmask_b32_e64 v2, 0, 1, s[28:29]
	s_cselect_b64 s[30:31], -1, 0
	v_readfirstlane_b32 s20, v2
	s_cmp_lg_u64 s[30:31], 0
	s_addc_u32 s16, s16, s20
	s_cmpk_gt_i32 s56, 0x15bf
	s_cselect_b64 s[34:35], -1, 0
	s_cmpk_gt_i32 s56, 0x167f
	v_cndmask_b32_e64 v2, 0, 1, s[34:35]
	s_cselect_b64 s[36:37], -1, 0
	v_readfirstlane_b32 s20, v2
	s_cmp_lg_u64 s[36:37], 0
	s_addc_u32 s16, s16, s20
	s_cmpk_gt_i32 s56, 0x16bf
	s_cselect_b64 s[38:39], -1, 0
	s_cmpk_gt_i32 s56, 0x16df
	v_cndmask_b32_e64 v2, 0, 1, s[38:39]
	s_cselect_b64 s[40:41], -1, 0
	v_readfirstlane_b32 s20, v2
	s_cmp_lg_u64 s[40:41], 0
	s_addc_u32 s62, s16, s20
	s_cmp_lg_u32 s62, 1
	s_cbranch_scc1 .LBB0_1403
	s_mov_b64 s[20:21], 0x1b00000
	s_mov_b32 s16, -1
	s_movk_i32 s60, 0x800
	s_mov_b64 s[46:47], 14
	s_mov_b64 s[22:23], 0
	s_cmp_lg_u32 s62, 2
	s_mov_b64 s[44:45], 0
	s_cbranch_scc0 .LBB0_1404
	s_branch .LBB0_1405
